# P3 epilogues: flat loads/stores replaced by global (no lgkmcnt coupling with the next unit's first LDS waits)
# speedup vs baseline: 1.0124x; 1.0008x over previous
.LBB0_603:
	s_cmp_gt_i32 s87, 2
	s_mov_b64 s[58:59], -1
	s_cbranch_scc0 .LBB0_605
	s_lshl_b64 s[58:59], s[56:57], 1
	s_mov_b32 s7, s3
	v_mov_b32_e32 v159, v0
	s_add_i32 s99, s98, 2
	s_lshl_b32 s99, s99, 17
	s_add_u32 s100, s38, 0xba00000
	s_addc_u32 s101, s39, 0
	s_add_u32 s100, s100, s99
	s_addc_u32 s101, s101, 0
	v_lshrrev_b32_e32 v2, 6, v175
	v_mul_u32_u24_e32 v2, 0x3c00, v2
	v_lshl_add_u32 v2, v175, 4, v2
	v_mov_b32_e32 v3, 0
	v_lshl_add_u64 v[2:3], s[100:101], 0, v[2:3]
	v_lshlrev_b64 v[140:141], 12, v[164:165]
	v_add_co_u32_e32 v132, vcc, 0, v2
	v_lshl_add_u64 v[140:141], s[10:11], 0, v[140:141]
	s_nop 0
	v_addc_co_u32_e32 v133, vcc, 0, v3, vcc
	v_lshl_add_u64 v[140:141], v[140:141], 0, s[58:59]
	global_load_dwordx4 v[132:135], v[132:133], off
	v_lshl_add_u64 v[136:137], v[2:3], 0, s[24:25]
	v_lshl_add_u64 v[140:141], v[140:141], 0, s[6:7]
	global_load_dwordx4 v[136:139], v[136:137], off offset:1024
	v_lshl_add_u64 v[168:169], v[140:141], 0, v[158:159]
	v_lshl_add_u64 v[2:3], v[2:3], 0, s[26:27]
	global_load_dwordx4 v[140:143], v[2:3], off
	global_load_dwordx4 v[164:167], v[2:3], off offset:1024
	v_lshl_add_u64 v[170:171], v[168:169], 0, s[46:47]
	v_lshl_add_u64 v[2:3], v[2:3], 0, s[20:21]
	s_waitcnt vmcnt(0)
	v_lshlrev_b32_e32 v178, 16, v132
	v_and_b32_e32 v179, 0xffff0000, v132
	v_lshlrev_b32_e32 v132, 16, v133
	v_and_b32_e32 v133, 0xffff0000, v133
	v_lshlrev_b32_e32 v180, 16, v134
	v_and_b32_e32 v181, 0xffff0000, v134
	v_lshlrev_b32_e32 v134, 16, v135
	v_and_b32_e32 v135, 0xffff0000, v135
	v_lshlrev_b32_e32 v182, 16, v136
	v_and_b32_e32 v183, 0xffff0000, v136
	v_lshlrev_b32_e32 v136, 16, v137
	v_and_b32_e32 v137, 0xffff0000, v137
	v_lshlrev_b32_e32 v184, 16, v138
	v_and_b32_e32 v185, 0xffff0000, v138
	v_lshlrev_b32_e32 v138, 16, v139
	v_and_b32_e32 v139, 0xffff0000, v139
	v_pk_mul_f32 v[178:179], v[128:129], v[178:179]
	v_pk_mul_f32 v[188:189], v[130:131], v[132:133]
	v_pk_mul_f32 v[180:181], v[124:125], v[180:181]
	v_pk_mul_f32 v[190:191], v[126:127], v[134:135]
	v_pk_mul_f32 v[182:183], v[120:121], v[182:183]
	v_pk_mul_f32 v[192:193], v[122:123], v[136:137]
	v_pk_mul_f32 v[184:185], v[116:117], v[184:185]
	v_pk_mul_f32 v[194:195], v[118:119], v[138:139]
	v_cvt_pk_bf16_f32 v132, v178, v179
	v_cvt_pk_bf16_f32 v133, v188, v189
	v_cvt_pk_bf16_f32 v134, v180, v181
	v_cvt_pk_bf16_f32 v135, v190, v191
	v_cvt_pk_bf16_f32 v136, v182, v183
	v_cvt_pk_bf16_f32 v137, v192, v193
	v_cvt_pk_bf16_f32 v138, v184, v185
	v_cvt_pk_bf16_f32 v139, v194, v195
	global_store_dwordx4 v[168:169], v[132:135], off
	global_store_dwordx4 v[168:169], v[136:139], off offset:256
	s_waitcnt lgkmcnt(0)
	v_lshlrev_b32_e32 v168, 16, v140
	v_and_b32_e32 v169, 0xffff0000, v140
	v_lshlrev_b32_e32 v140, 16, v141
	v_and_b32_e32 v141, 0xffff0000, v141
	v_lshlrev_b32_e32 v178, 16, v142
	v_and_b32_e32 v179, 0xffff0000, v142
	v_lshlrev_b32_e32 v142, 16, v143
	v_and_b32_e32 v143, 0xffff0000, v143
	v_lshlrev_b32_e32 v180, 16, v164
	v_and_b32_e32 v181, 0xffff0000, v164
	v_lshlrev_b32_e32 v164, 16, v165
	v_and_b32_e32 v165, 0xffff0000, v165
	v_lshlrev_b32_e32 v182, 16, v166
	v_and_b32_e32 v183, 0xffff0000, v166
	v_lshlrev_b32_e32 v166, 16, v167
	v_and_b32_e32 v167, 0xffff0000, v167
	v_pk_mul_f32 v[168:169], v[112:113], v[168:169]
	v_pk_mul_f32 v[184:185], v[114:115], v[140:141]
	v_pk_mul_f32 v[178:179], v[108:109], v[178:179]
	v_pk_mul_f32 v[188:189], v[110:111], v[142:143]
	global_load_dwordx4 v[132:135], v[2:3], off
	global_load_dwordx4 v[136:139], v[2:3], off offset:1024
	v_pk_mul_f32 v[180:181], v[104:105], v[180:181]
	v_pk_mul_f32 v[190:191], v[106:107], v[164:165]
	v_pk_mul_f32 v[182:183], v[100:101], v[182:183]
	v_pk_mul_f32 v[192:193], v[102:103], v[166:167]
	v_cvt_pk_bf16_f32 v140, v168, v169
	v_cvt_pk_bf16_f32 v141, v184, v185
	v_cvt_pk_bf16_f32 v142, v178, v179
	v_cvt_pk_bf16_f32 v143, v188, v189
	v_cvt_pk_bf16_f32 v164, v180, v181
	v_cvt_pk_bf16_f32 v165, v190, v191
	v_cvt_pk_bf16_f32 v166, v182, v183
	v_cvt_pk_bf16_f32 v167, v192, v193
	global_store_dwordx4 v[170:171], v[140:143], off
	global_store_dwordx4 v[170:171], v[164:167], off offset:256
	v_lshl_add_u64 v[168:169], v[170:171], 0, s[46:47]
	v_lshl_add_u64 v[2:3], v[2:3], 0, s[20:21]
	global_load_dwordx4 v[140:143], v[2:3], off
	global_load_dwordx4 v[164:167], v[2:3], off offset:1024
	v_lshl_add_u64 v[170:171], v[168:169], 0, s[46:47]
	v_lshl_add_u64 v[2:3], v[2:3], 0, s[22:23]
	s_waitcnt vmcnt(0) lgkmcnt(0)
	v_lshlrev_b32_e32 v178, 16, v132
	v_and_b32_e32 v179, 0xffff0000, v132
	v_lshlrev_b32_e32 v132, 16, v133
	v_and_b32_e32 v133, 0xffff0000, v133
	v_lshlrev_b32_e32 v180, 16, v134
	v_and_b32_e32 v181, 0xffff0000, v134
	v_lshlrev_b32_e32 v134, 16, v135
	v_and_b32_e32 v135, 0xffff0000, v135
	v_lshlrev_b32_e32 v182, 16, v136
	v_and_b32_e32 v183, 0xffff0000, v136
	v_lshlrev_b32_e32 v136, 16, v137
	v_and_b32_e32 v137, 0xffff0000, v137
	v_lshlrev_b32_e32 v184, 16, v138
	v_and_b32_e32 v185, 0xffff0000, v138
	v_lshlrev_b32_e32 v138, 16, v139
	v_and_b32_e32 v139, 0xffff0000, v139
	v_pk_mul_f32 v[178:179], v[96:97], v[178:179]
	v_pk_mul_f32 v[188:189], v[98:99], v[132:133]
	v_pk_mul_f32 v[180:181], v[92:93], v[180:181]
	v_pk_mul_f32 v[190:191], v[94:95], v[134:135]
	v_pk_mul_f32 v[182:183], v[88:89], v[182:183]
	v_pk_mul_f32 v[192:193], v[90:91], v[136:137]
	v_pk_mul_f32 v[184:185], v[84:85], v[184:185]
	v_pk_mul_f32 v[194:195], v[86:87], v[138:139]
	v_cvt_pk_bf16_f32 v132, v178, v179
	v_cvt_pk_bf16_f32 v133, v188, v189
	v_cvt_pk_bf16_f32 v134, v180, v181
	v_cvt_pk_bf16_f32 v135, v190, v191
	v_cvt_pk_bf16_f32 v136, v182, v183
	v_cvt_pk_bf16_f32 v137, v192, v193
	v_cvt_pk_bf16_f32 v138, v184, v185
	v_cvt_pk_bf16_f32 v139, v194, v195
	global_store_dwordx4 v[168:169], v[132:135], off
	global_store_dwordx4 v[168:169], v[136:139], off offset:256
	v_lshlrev_b32_e32 v168, 16, v140
	v_and_b32_e32 v169, 0xffff0000, v140
	v_lshlrev_b32_e32 v140, 16, v141
	v_and_b32_e32 v141, 0xffff0000, v141
	v_lshlrev_b32_e32 v178, 16, v142
	v_and_b32_e32 v179, 0xffff0000, v142
	v_lshlrev_b32_e32 v142, 16, v143
	v_and_b32_e32 v143, 0xffff0000, v143
	v_lshlrev_b32_e32 v180, 16, v164
	v_and_b32_e32 v181, 0xffff0000, v164
	v_lshlrev_b32_e32 v164, 16, v165
	v_and_b32_e32 v165, 0xffff0000, v165
	v_lshlrev_b32_e32 v182, 16, v166
	v_and_b32_e32 v183, 0xffff0000, v166
	v_lshlrev_b32_e32 v166, 16, v167
	v_and_b32_e32 v167, 0xffff0000, v167
	v_pk_mul_f32 v[168:169], v[80:81], v[168:169]
	v_pk_mul_f32 v[184:185], v[82:83], v[140:141]
	v_pk_mul_f32 v[178:179], v[76:77], v[178:179]
	v_pk_mul_f32 v[188:189], v[78:79], v[142:143]
	global_load_dwordx4 v[132:135], v[2:3], off
	global_load_dwordx4 v[136:139], v[2:3], off offset:1024
	v_pk_mul_f32 v[180:181], v[72:73], v[180:181]
	v_pk_mul_f32 v[190:191], v[74:75], v[164:165]
	v_pk_mul_f32 v[182:183], v[68:69], v[182:183]
	v_pk_mul_f32 v[192:193], v[70:71], v[166:167]
	v_cvt_pk_bf16_f32 v140, v168, v169
	v_cvt_pk_bf16_f32 v141, v184, v185
	v_cvt_pk_bf16_f32 v142, v178, v179
	v_cvt_pk_bf16_f32 v143, v188, v189
	v_cvt_pk_bf16_f32 v164, v180, v181
	v_cvt_pk_bf16_f32 v165, v190, v191
	v_cvt_pk_bf16_f32 v166, v182, v183
	v_cvt_pk_bf16_f32 v167, v192, v193
	global_store_dwordx4 v[170:171], v[140:143], off
	global_store_dwordx4 v[170:171], v[164:167], off offset:256
	v_lshl_add_u64 v[168:169], v[170:171], 0, s[48:49]
	v_lshl_add_u64 v[2:3], v[2:3], 0, s[20:21]
	global_load_dwordx4 v[140:143], v[2:3], off
	global_load_dwordx4 v[164:167], v[2:3], off offset:1024
	v_lshl_add_u64 v[170:171], v[168:169], 0, s[46:47]
	v_lshl_add_u64 v[2:3], v[2:3], 0, s[20:21]
	s_waitcnt vmcnt(0) lgkmcnt(0)
	v_lshlrev_b32_e32 v178, 16, v132
	v_and_b32_e32 v179, 0xffff0000, v132
	v_lshlrev_b32_e32 v132, 16, v133
	v_and_b32_e32 v133, 0xffff0000, v133
	v_lshlrev_b32_e32 v180, 16, v134
	v_and_b32_e32 v181, 0xffff0000, v134
	v_lshlrev_b32_e32 v134, 16, v135
	v_and_b32_e32 v135, 0xffff0000, v135
	v_lshlrev_b32_e32 v182, 16, v136
	v_and_b32_e32 v183, 0xffff0000, v136
	v_lshlrev_b32_e32 v136, 16, v137
	v_and_b32_e32 v137, 0xffff0000, v137
	v_lshlrev_b32_e32 v184, 16, v138
	v_and_b32_e32 v185, 0xffff0000, v138
	v_lshlrev_b32_e32 v138, 16, v139
	v_and_b32_e32 v139, 0xffff0000, v139
	v_pk_mul_f32 v[178:179], v[64:65], v[178:179]
	v_pk_mul_f32 v[188:189], v[66:67], v[132:133]
	v_pk_mul_f32 v[180:181], v[60:61], v[180:181]
	v_pk_mul_f32 v[190:191], v[62:63], v[134:135]
	v_pk_mul_f32 v[182:183], v[56:57], v[182:183]
	v_pk_mul_f32 v[192:193], v[58:59], v[136:137]
	v_pk_mul_f32 v[184:185], v[52:53], v[184:185]
	v_pk_mul_f32 v[194:195], v[54:55], v[138:139]
	v_cvt_pk_bf16_f32 v132, v178, v179
	v_cvt_pk_bf16_f32 v133, v188, v189
	v_cvt_pk_bf16_f32 v134, v180, v181
	v_cvt_pk_bf16_f32 v135, v190, v191
	v_cvt_pk_bf16_f32 v136, v182, v183
	v_cvt_pk_bf16_f32 v137, v192, v193
	v_cvt_pk_bf16_f32 v138, v184, v185
	v_cvt_pk_bf16_f32 v139, v194, v195
	global_store_dwordx4 v[168:169], v[132:135], off
	global_store_dwordx4 v[168:169], v[136:139], off offset:256
	v_lshlrev_b32_e32 v168, 16, v140
	v_and_b32_e32 v169, 0xffff0000, v140
	v_lshlrev_b32_e32 v140, 16, v141
	v_and_b32_e32 v141, 0xffff0000, v141
	v_lshlrev_b32_e32 v178, 16, v142
	v_and_b32_e32 v179, 0xffff0000, v142
	v_lshlrev_b32_e32 v142, 16, v143
	v_and_b32_e32 v143, 0xffff0000, v143
	v_lshlrev_b32_e32 v180, 16, v164
	v_and_b32_e32 v181, 0xffff0000, v164
	v_lshlrev_b32_e32 v164, 16, v165
	v_and_b32_e32 v165, 0xffff0000, v165
	v_lshlrev_b32_e32 v182, 16, v166
	v_and_b32_e32 v183, 0xffff0000, v166
	v_lshlrev_b32_e32 v166, 16, v167
	v_and_b32_e32 v167, 0xffff0000, v167
	v_pk_mul_f32 v[168:169], v[48:49], v[168:169]
	v_pk_mul_f32 v[184:185], v[50:51], v[140:141]
	v_pk_mul_f32 v[178:179], v[44:45], v[178:179]
	v_pk_mul_f32 v[188:189], v[46:47], v[142:143]
	v_pk_mul_f32 v[180:181], v[40:41], v[180:181]
	v_pk_mul_f32 v[190:191], v[42:43], v[164:165]
	v_pk_mul_f32 v[182:183], v[36:37], v[182:183]
	v_pk_mul_f32 v[192:193], v[38:39], v[166:167]
	v_cvt_pk_bf16_f32 v140, v168, v169
	v_cvt_pk_bf16_f32 v141, v184, v185
	v_cvt_pk_bf16_f32 v142, v178, v179
	v_cvt_pk_bf16_f32 v143, v188, v189
	global_load_dwordx4 v[132:135], v[2:3], off
	global_load_dwordx4 v[136:139], v[2:3], off offset:1024
	v_cvt_pk_bf16_f32 v164, v180, v181
	v_cvt_pk_bf16_f32 v165, v190, v191
	v_cvt_pk_bf16_f32 v166, v182, v183
	v_cvt_pk_bf16_f32 v167, v192, v193
	global_store_dwordx4 v[170:171], v[140:143], off
	global_store_dwordx4 v[170:171], v[164:167], off offset:256
	v_lshl_add_u64 v[168:169], v[170:171], 0, s[46:47]
	v_lshl_add_u64 v[170:171], v[2:3], 0, s[20:21]
	global_load_dwordx4 v[140:143], v[170:171], off
	global_load_dwordx4 v[164:167], v[170:171], off offset:1024
	v_lshl_add_u64 v[2:3], v[168:169], 0, s[46:47]
	v_lshl_add_u64 v[170:171], v[170:171], 0, s[22:23]
	s_waitcnt vmcnt(0) lgkmcnt(0)
	v_lshlrev_b32_e32 v178, 16, v132
	v_and_b32_e32 v179, 0xffff0000, v132
	v_lshlrev_b32_e32 v132, 16, v133
	v_and_b32_e32 v133, 0xffff0000, v133
	v_lshlrev_b32_e32 v180, 16, v134
	v_and_b32_e32 v181, 0xffff0000, v134
	v_lshlrev_b32_e32 v134, 16, v135
	v_and_b32_e32 v135, 0xffff0000, v135
	v_lshlrev_b32_e32 v182, 16, v136
	v_and_b32_e32 v183, 0xffff0000, v136
	v_lshlrev_b32_e32 v136, 16, v137
	v_and_b32_e32 v137, 0xffff0000, v137
	v_lshlrev_b32_e32 v184, 16, v138
	v_and_b32_e32 v185, 0xffff0000, v138
	v_lshlrev_b32_e32 v138, 16, v139
	v_and_b32_e32 v139, 0xffff0000, v139
	v_pk_mul_f32 v[178:179], v[32:33], v[178:179]
	v_pk_mul_f32 v[188:189], v[34:35], v[132:133]
	v_pk_mul_f32 v[180:181], v[28:29], v[180:181]
	v_pk_mul_f32 v[190:191], v[30:31], v[134:135]
	v_pk_mul_f32 v[182:183], v[24:25], v[182:183]
	v_pk_mul_f32 v[192:193], v[26:27], v[136:137]
	v_pk_mul_f32 v[184:185], v[20:21], v[184:185]
	v_pk_mul_f32 v[194:195], v[22:23], v[138:139]
	v_cvt_pk_bf16_f32 v132, v178, v179
	v_cvt_pk_bf16_f32 v133, v188, v189
	v_cvt_pk_bf16_f32 v134, v180, v181
	v_cvt_pk_bf16_f32 v135, v190, v191
	v_cvt_pk_bf16_f32 v136, v182, v183
	v_cvt_pk_bf16_f32 v137, v192, v193
	v_cvt_pk_bf16_f32 v138, v184, v185
	v_cvt_pk_bf16_f32 v139, v194, v195
	global_store_dwordx4 v[168:169], v[132:135], off
	global_store_dwordx4 v[168:169], v[136:139], off offset:256
	s_nop 0
	v_lshlrev_b32_e32 v132, 16, v140
	v_and_b32_e32 v133, 0xffff0000, v140
	v_lshlrev_b32_e32 v134, 16, v141
	v_and_b32_e32 v135, 0xffff0000, v141
	v_lshlrev_b32_e32 v136, 16, v142
	v_and_b32_e32 v137, 0xffff0000, v142
	v_lshlrev_b32_e32 v138, 16, v143
	v_and_b32_e32 v139, 0xffff0000, v143
	v_lshlrev_b32_e32 v140, 16, v164
	v_and_b32_e32 v141, 0xffff0000, v164
	v_lshlrev_b32_e32 v142, 16, v165
	v_and_b32_e32 v143, 0xffff0000, v165
	v_lshlrev_b32_e32 v164, 16, v166
	v_and_b32_e32 v165, 0xffff0000, v166
	v_pk_mul_f32 v[132:133], v[16:17], v[132:133]
	v_pk_mul_f32 v[134:135], v[18:19], v[134:135]
	v_pk_mul_f32 v[168:169], v[12:13], v[136:137]
	v_pk_mul_f32 v[170:171], v[14:15], v[138:139]
	v_lshlrev_b32_e32 v166, 16, v167
	v_and_b32_e32 v167, 0xffff0000, v167
	v_pk_mul_f32 v[178:179], v[8:9], v[140:141]
	v_pk_mul_f32 v[142:143], v[10:11], v[142:143]
	v_pk_mul_f32 v[164:165], v[4:5], v[164:165]
	v_cvt_pk_bf16_f32 v138, v132, v133
	v_cvt_pk_bf16_f32 v139, v134, v135
	v_cvt_pk_bf16_f32 v140, v168, v169
	v_cvt_pk_bf16_f32 v141, v170, v171
	v_pk_mul_f32 v[136:137], v[6:7], v[166:167]
	v_cvt_pk_bf16_f32 v132, v178, v179
	v_cvt_pk_bf16_f32 v133, v142, v143
	v_cvt_pk_bf16_f32 v134, v164, v165
	global_store_dwordx4 v[2:3], v[138:141], off
	s_cbranch_execz .LBB0_606
	s_branch .LBB0_607

.LBB0_606:
	s_add_i32 s99, s98, s87
	s_lshl_b32 s99, s99, 17
	s_add_u32 s100, s38, 0xba00000
	s_addc_u32 s101, s39, 0
	s_add_u32 s100, s100, s99
	s_addc_u32 s101, s101, 0
	v_lshrrev_b32_e32 v2, 6, v175
	v_mul_u32_u24_e32 v2, 0x3c00, v2
	v_lshl_add_u32 v2, v175, 4, v2
	v_mov_b32_e32 v3, 0
	v_lshl_add_u64 v[2:3], s[100:101], 0, v[2:3]
	s_mov_b32 s100, 0xbfb8aa3b
	s_mov_b32 s101, 0xbfb8aa3b
	v_med3_f32 v128, v128, s81, v176
	v_med3_f32 v129, v129, s81, v176
	v_med3_f32 v130, v130, s81, v176
	v_med3_f32 v131, v131, s81, v176
	v_med3_f32 v124, v124, s81, v176
	v_med3_f32 v125, v125, s81, v176
	v_med3_f32 v126, v126, s81, v176
	v_med3_f32 v127, v127, s81, v176
	v_pk_mul_f32 v[128:129], v[128:129], s[100:101] op_sel_hi:[1,0]
	v_pk_mul_f32 v[130:131], v[130:131], s[100:101] op_sel_hi:[1,0]
	v_pk_mul_f32 v[124:125], v[124:125], s[100:101] op_sel_hi:[1,0]
	v_pk_mul_f32 v[126:127], v[126:127], s[100:101] op_sel_hi:[1,0]
	v_exp_f32_e32 v128, v128
	v_exp_f32_e32 v129, v129
	v_exp_f32_e32 v130, v130
	v_exp_f32_e32 v131, v131
	v_exp_f32_e32 v124, v124
	v_exp_f32_e32 v125, v125
	v_exp_f32_e32 v126, v126
	v_exp_f32_e32 v127, v127
	v_pk_add_f32 v[128:129], v[128:129], 1.0 op_sel_hi:[1,0]
	v_pk_add_f32 v[130:131], v[130:131], 1.0 op_sel_hi:[1,0]
	v_pk_add_f32 v[124:125], v[124:125], 1.0 op_sel_hi:[1,0]
	v_pk_add_f32 v[126:127], v[126:127], 1.0 op_sel_hi:[1,0]
	v_rcp_f32_e32 v128, v128
	v_rcp_f32_e32 v129, v129
	v_rcp_f32_e32 v130, v130
	v_rcp_f32_e32 v131, v131
	v_rcp_f32_e32 v124, v124
	v_rcp_f32_e32 v125, v125
	v_rcp_f32_e32 v126, v126
	v_rcp_f32_e32 v127, v127
	v_cvt_pk_bf16_f32 v132, v128, v129
	v_cvt_pk_bf16_f32 v133, v130, v131
	v_cvt_pk_bf16_f32 v134, v124, v125
	v_cvt_pk_bf16_f32 v135, v126, v127
	global_store_dwordx4 v[2:3], v[132:135], off
	v_med3_f32 v120, v120, s81, v176
	v_med3_f32 v121, v121, s81, v176
	v_med3_f32 v122, v122, s81, v176
	v_med3_f32 v123, v123, s81, v176
	v_med3_f32 v116, v116, s81, v176
	v_med3_f32 v117, v117, s81, v176
	v_med3_f32 v118, v118, s81, v176
	v_med3_f32 v119, v119, s81, v176
	v_pk_mul_f32 v[120:121], v[120:121], s[100:101] op_sel_hi:[1,0]
	v_pk_mul_f32 v[122:123], v[122:123], s[100:101] op_sel_hi:[1,0]
	v_pk_mul_f32 v[116:117], v[116:117], s[100:101] op_sel_hi:[1,0]
	v_pk_mul_f32 v[118:119], v[118:119], s[100:101] op_sel_hi:[1,0]
	v_exp_f32_e32 v120, v120
	v_exp_f32_e32 v121, v121
	v_exp_f32_e32 v122, v122
	v_exp_f32_e32 v123, v123
	v_exp_f32_e32 v116, v116
	v_exp_f32_e32 v117, v117
	v_exp_f32_e32 v118, v118
	v_exp_f32_e32 v119, v119
	v_pk_add_f32 v[120:121], v[120:121], 1.0 op_sel_hi:[1,0]
	v_pk_add_f32 v[122:123], v[122:123], 1.0 op_sel_hi:[1,0]
	v_pk_add_f32 v[116:117], v[116:117], 1.0 op_sel_hi:[1,0]
	v_pk_add_f32 v[118:119], v[118:119], 1.0 op_sel_hi:[1,0]
	v_rcp_f32_e32 v120, v120
	v_rcp_f32_e32 v121, v121
	v_rcp_f32_e32 v122, v122
	v_rcp_f32_e32 v123, v123
	v_rcp_f32_e32 v116, v116
	v_rcp_f32_e32 v117, v117
	v_rcp_f32_e32 v118, v118
	v_rcp_f32_e32 v119, v119
	v_cvt_pk_bf16_f32 v140, v120, v121
	v_cvt_pk_bf16_f32 v141, v122, v123
	v_cvt_pk_bf16_f32 v142, v116, v117
	v_cvt_pk_bf16_f32 v143, v118, v119
	global_store_dwordx4 v[2:3], v[140:143], off offset:1024
	v_lshl_add_u64 v[2:3], v[2:3], 0, s[20:21]
	v_med3_f32 v112, v112, s81, v176
	v_med3_f32 v113, v113, s81, v176
	v_med3_f32 v114, v114, s81, v176
	v_med3_f32 v115, v115, s81, v176
	v_med3_f32 v108, v108, s81, v176
	v_med3_f32 v109, v109, s81, v176
	v_med3_f32 v110, v110, s81, v176
	v_med3_f32 v111, v111, s81, v176
	v_pk_mul_f32 v[112:113], v[112:113], s[100:101] op_sel_hi:[1,0]
	v_pk_mul_f32 v[114:115], v[114:115], s[100:101] op_sel_hi:[1,0]
	v_pk_mul_f32 v[108:109], v[108:109], s[100:101] op_sel_hi:[1,0]
	v_pk_mul_f32 v[110:111], v[110:111], s[100:101] op_sel_hi:[1,0]
	v_exp_f32_e32 v112, v112
	v_exp_f32_e32 v113, v113
	v_exp_f32_e32 v114, v114
	v_exp_f32_e32 v115, v115
	v_exp_f32_e32 v108, v108
	v_exp_f32_e32 v109, v109
	v_exp_f32_e32 v110, v110
	v_exp_f32_e32 v111, v111
	v_pk_add_f32 v[112:113], v[112:113], 1.0 op_sel_hi:[1,0]
	v_pk_add_f32 v[114:115], v[114:115], 1.0 op_sel_hi:[1,0]
	v_pk_add_f32 v[108:109], v[108:109], 1.0 op_sel_hi:[1,0]
	v_pk_add_f32 v[110:111], v[110:111], 1.0 op_sel_hi:[1,0]
	v_rcp_f32_e32 v112, v112
	v_rcp_f32_e32 v113, v113
	v_rcp_f32_e32 v114, v114
	v_rcp_f32_e32 v115, v115
	v_rcp_f32_e32 v108, v108
	v_rcp_f32_e32 v109, v109
	v_rcp_f32_e32 v110, v110
	v_rcp_f32_e32 v111, v111
	v_cvt_pk_bf16_f32 v132, v112, v113
	v_cvt_pk_bf16_f32 v133, v114, v115
	v_cvt_pk_bf16_f32 v134, v108, v109
	v_cvt_pk_bf16_f32 v135, v110, v111
	global_store_dwordx4 v[2:3], v[132:135], off
	v_med3_f32 v104, v104, s81, v176
	v_med3_f32 v105, v105, s81, v176
	v_med3_f32 v106, v106, s81, v176
	v_med3_f32 v107, v107, s81, v176
	v_med3_f32 v100, v100, s81, v176
	v_med3_f32 v101, v101, s81, v176
	v_med3_f32 v102, v102, s81, v176
	v_med3_f32 v103, v103, s81, v176
	v_pk_mul_f32 v[104:105], v[104:105], s[100:101] op_sel_hi:[1,0]
	v_pk_mul_f32 v[106:107], v[106:107], s[100:101] op_sel_hi:[1,0]
	v_pk_mul_f32 v[100:101], v[100:101], s[100:101] op_sel_hi:[1,0]
	v_pk_mul_f32 v[102:103], v[102:103], s[100:101] op_sel_hi:[1,0]
	v_exp_f32_e32 v104, v104
	v_exp_f32_e32 v105, v105
	v_exp_f32_e32 v106, v106
	v_exp_f32_e32 v107, v107
	v_exp_f32_e32 v100, v100
	v_exp_f32_e32 v101, v101
	v_exp_f32_e32 v102, v102
	v_exp_f32_e32 v103, v103
	v_pk_add_f32 v[104:105], v[104:105], 1.0 op_sel_hi:[1,0]
	v_pk_add_f32 v[106:107], v[106:107], 1.0 op_sel_hi:[1,0]
	v_pk_add_f32 v[100:101], v[100:101], 1.0 op_sel_hi:[1,0]
	v_pk_add_f32 v[102:103], v[102:103], 1.0 op_sel_hi:[1,0]
	v_rcp_f32_e32 v104, v104
	v_rcp_f32_e32 v105, v105
	v_rcp_f32_e32 v106, v106
	v_rcp_f32_e32 v107, v107
	v_rcp_f32_e32 v100, v100
	v_rcp_f32_e32 v101, v101
	v_rcp_f32_e32 v102, v102
	v_rcp_f32_e32 v103, v103
	v_cvt_pk_bf16_f32 v140, v104, v105
	v_cvt_pk_bf16_f32 v141, v106, v107
	v_cvt_pk_bf16_f32 v142, v100, v101
	v_cvt_pk_bf16_f32 v143, v102, v103
	global_store_dwordx4 v[2:3], v[140:143], off offset:1024
	v_lshl_add_u64 v[2:3], v[2:3], 0, s[20:21]
	v_med3_f32 v96, v96, s81, v176
	v_med3_f32 v97, v97, s81, v176
	v_med3_f32 v98, v98, s81, v176
	v_med3_f32 v99, v99, s81, v176
	v_med3_f32 v92, v92, s81, v176
	v_med3_f32 v93, v93, s81, v176
	v_med3_f32 v94, v94, s81, v176
	v_med3_f32 v95, v95, s81, v176
	v_pk_mul_f32 v[96:97], v[96:97], s[100:101] op_sel_hi:[1,0]
	v_pk_mul_f32 v[98:99], v[98:99], s[100:101] op_sel_hi:[1,0]
	v_pk_mul_f32 v[92:93], v[92:93], s[100:101] op_sel_hi:[1,0]
	v_pk_mul_f32 v[94:95], v[94:95], s[100:101] op_sel_hi:[1,0]
	v_exp_f32_e32 v96, v96
	v_exp_f32_e32 v97, v97
	v_exp_f32_e32 v98, v98
	v_exp_f32_e32 v99, v99
	v_exp_f32_e32 v92, v92
	v_exp_f32_e32 v93, v93
	v_exp_f32_e32 v94, v94
	v_exp_f32_e32 v95, v95
	v_pk_add_f32 v[96:97], v[96:97], 1.0 op_sel_hi:[1,0]
	v_pk_add_f32 v[98:99], v[98:99], 1.0 op_sel_hi:[1,0]
	v_pk_add_f32 v[92:93], v[92:93], 1.0 op_sel_hi:[1,0]
	v_pk_add_f32 v[94:95], v[94:95], 1.0 op_sel_hi:[1,0]
	v_rcp_f32_e32 v96, v96
	v_rcp_f32_e32 v97, v97
	v_rcp_f32_e32 v98, v98
	v_rcp_f32_e32 v99, v99
	v_rcp_f32_e32 v92, v92
	v_rcp_f32_e32 v93, v93
	v_rcp_f32_e32 v94, v94
	v_rcp_f32_e32 v95, v95
	v_cvt_pk_bf16_f32 v132, v96, v97
	v_cvt_pk_bf16_f32 v133, v98, v99
	v_cvt_pk_bf16_f32 v134, v92, v93
	v_cvt_pk_bf16_f32 v135, v94, v95
	global_store_dwordx4 v[2:3], v[132:135], off
	v_med3_f32 v88, v88, s81, v176
	v_med3_f32 v89, v89, s81, v176
	v_med3_f32 v90, v90, s81, v176
	v_med3_f32 v91, v91, s81, v176
	v_med3_f32 v84, v84, s81, v176
	v_med3_f32 v85, v85, s81, v176
	v_med3_f32 v86, v86, s81, v176
	v_med3_f32 v87, v87, s81, v176
	v_pk_mul_f32 v[88:89], v[88:89], s[100:101] op_sel_hi:[1,0]
	v_pk_mul_f32 v[90:91], v[90:91], s[100:101] op_sel_hi:[1,0]
	v_pk_mul_f32 v[84:85], v[84:85], s[100:101] op_sel_hi:[1,0]
	v_pk_mul_f32 v[86:87], v[86:87], s[100:101] op_sel_hi:[1,0]
	v_exp_f32_e32 v88, v88
	v_exp_f32_e32 v89, v89
	v_exp_f32_e32 v90, v90
	v_exp_f32_e32 v91, v91
	v_exp_f32_e32 v84, v84
	v_exp_f32_e32 v85, v85
	v_exp_f32_e32 v86, v86
	v_exp_f32_e32 v87, v87
	v_pk_add_f32 v[88:89], v[88:89], 1.0 op_sel_hi:[1,0]
	v_pk_add_f32 v[90:91], v[90:91], 1.0 op_sel_hi:[1,0]
	v_pk_add_f32 v[84:85], v[84:85], 1.0 op_sel_hi:[1,0]
	v_pk_add_f32 v[86:87], v[86:87], 1.0 op_sel_hi:[1,0]
	v_rcp_f32_e32 v88, v88
	v_rcp_f32_e32 v89, v89
	v_rcp_f32_e32 v90, v90
	v_rcp_f32_e32 v91, v91
	v_rcp_f32_e32 v84, v84
	v_rcp_f32_e32 v85, v85
	v_rcp_f32_e32 v86, v86
	v_rcp_f32_e32 v87, v87
	v_cvt_pk_bf16_f32 v140, v88, v89
	v_cvt_pk_bf16_f32 v141, v90, v91
	v_cvt_pk_bf16_f32 v142, v84, v85
	v_cvt_pk_bf16_f32 v143, v86, v87
	global_store_dwordx4 v[2:3], v[140:143], off offset:1024
	v_lshl_add_u64 v[2:3], v[2:3], 0, s[20:21]
	v_med3_f32 v80, v80, s81, v176
	v_med3_f32 v81, v81, s81, v176
	v_med3_f32 v82, v82, s81, v176
	v_med3_f32 v83, v83, s81, v176
	v_med3_f32 v76, v76, s81, v176
	v_med3_f32 v77, v77, s81, v176
	v_med3_f32 v78, v78, s81, v176
	v_med3_f32 v79, v79, s81, v176
	v_pk_mul_f32 v[80:81], v[80:81], s[100:101] op_sel_hi:[1,0]
	v_pk_mul_f32 v[82:83], v[82:83], s[100:101] op_sel_hi:[1,0]
	v_pk_mul_f32 v[76:77], v[76:77], s[100:101] op_sel_hi:[1,0]
	v_pk_mul_f32 v[78:79], v[78:79], s[100:101] op_sel_hi:[1,0]
	v_exp_f32_e32 v80, v80
	v_exp_f32_e32 v81, v81
	v_exp_f32_e32 v82, v82
	v_exp_f32_e32 v83, v83
	v_exp_f32_e32 v76, v76
	v_exp_f32_e32 v77, v77
	v_exp_f32_e32 v78, v78
	v_exp_f32_e32 v79, v79
	v_pk_add_f32 v[80:81], v[80:81], 1.0 op_sel_hi:[1,0]
	v_pk_add_f32 v[82:83], v[82:83], 1.0 op_sel_hi:[1,0]
	v_pk_add_f32 v[76:77], v[76:77], 1.0 op_sel_hi:[1,0]
	v_pk_add_f32 v[78:79], v[78:79], 1.0 op_sel_hi:[1,0]
	v_rcp_f32_e32 v80, v80
	v_rcp_f32_e32 v81, v81
	v_rcp_f32_e32 v82, v82
	v_rcp_f32_e32 v83, v83
	v_rcp_f32_e32 v76, v76
	v_rcp_f32_e32 v77, v77
	v_rcp_f32_e32 v78, v78
	v_rcp_f32_e32 v79, v79
	v_cvt_pk_bf16_f32 v132, v80, v81
	v_cvt_pk_bf16_f32 v133, v82, v83
	v_cvt_pk_bf16_f32 v134, v76, v77
	v_cvt_pk_bf16_f32 v135, v78, v79
	global_store_dwordx4 v[2:3], v[132:135], off
	v_med3_f32 v72, v72, s81, v176
	v_med3_f32 v73, v73, s81, v176
	v_med3_f32 v74, v74, s81, v176
	v_med3_f32 v75, v75, s81, v176
	v_med3_f32 v68, v68, s81, v176
	v_med3_f32 v69, v69, s81, v176
	v_med3_f32 v70, v70, s81, v176
	v_med3_f32 v71, v71, s81, v176
	v_pk_mul_f32 v[72:73], v[72:73], s[100:101] op_sel_hi:[1,0]
	v_pk_mul_f32 v[74:75], v[74:75], s[100:101] op_sel_hi:[1,0]
	v_pk_mul_f32 v[68:69], v[68:69], s[100:101] op_sel_hi:[1,0]
	v_pk_mul_f32 v[70:71], v[70:71], s[100:101] op_sel_hi:[1,0]
	v_exp_f32_e32 v72, v72
	v_exp_f32_e32 v73, v73
	v_exp_f32_e32 v74, v74
	v_exp_f32_e32 v75, v75
	v_exp_f32_e32 v68, v68
	v_exp_f32_e32 v69, v69
	v_exp_f32_e32 v70, v70
	v_exp_f32_e32 v71, v71
	v_pk_add_f32 v[72:73], v[72:73], 1.0 op_sel_hi:[1,0]
	v_pk_add_f32 v[74:75], v[74:75], 1.0 op_sel_hi:[1,0]
	v_pk_add_f32 v[68:69], v[68:69], 1.0 op_sel_hi:[1,0]
	v_pk_add_f32 v[70:71], v[70:71], 1.0 op_sel_hi:[1,0]
	v_rcp_f32_e32 v72, v72
	v_rcp_f32_e32 v73, v73
	v_rcp_f32_e32 v74, v74
	v_rcp_f32_e32 v75, v75
	v_rcp_f32_e32 v68, v68
	v_rcp_f32_e32 v69, v69
	v_rcp_f32_e32 v70, v70
	v_rcp_f32_e32 v71, v71
	v_cvt_pk_bf16_f32 v140, v72, v73
	v_cvt_pk_bf16_f32 v141, v74, v75
	v_cvt_pk_bf16_f32 v142, v68, v69
	v_cvt_pk_bf16_f32 v143, v70, v71
	global_store_dwordx4 v[2:3], v[140:143], off offset:1024
	v_lshl_add_u64 v[2:3], v[2:3], 0, s[20:21]
	v_med3_f32 v64, v64, s81, v176
	v_med3_f32 v65, v65, s81, v176
	v_med3_f32 v66, v66, s81, v176
	v_med3_f32 v67, v67, s81, v176
	v_med3_f32 v60, v60, s81, v176
	v_med3_f32 v61, v61, s81, v176
	v_med3_f32 v62, v62, s81, v176
	v_med3_f32 v63, v63, s81, v176
	v_pk_mul_f32 v[64:65], v[64:65], s[100:101] op_sel_hi:[1,0]
	v_pk_mul_f32 v[66:67], v[66:67], s[100:101] op_sel_hi:[1,0]
	v_pk_mul_f32 v[60:61], v[60:61], s[100:101] op_sel_hi:[1,0]
	v_pk_mul_f32 v[62:63], v[62:63], s[100:101] op_sel_hi:[1,0]
	v_exp_f32_e32 v64, v64
	v_exp_f32_e32 v65, v65
	v_exp_f32_e32 v66, v66
	v_exp_f32_e32 v67, v67
	v_exp_f32_e32 v60, v60
	v_exp_f32_e32 v61, v61
	v_exp_f32_e32 v62, v62
	v_exp_f32_e32 v63, v63
	v_pk_add_f32 v[64:65], v[64:65], 1.0 op_sel_hi:[1,0]
	v_pk_add_f32 v[66:67], v[66:67], 1.0 op_sel_hi:[1,0]
	v_pk_add_f32 v[60:61], v[60:61], 1.0 op_sel_hi:[1,0]
	v_pk_add_f32 v[62:63], v[62:63], 1.0 op_sel_hi:[1,0]
	v_rcp_f32_e32 v64, v64
	v_rcp_f32_e32 v65, v65
	v_rcp_f32_e32 v66, v66
	v_rcp_f32_e32 v67, v67
	v_rcp_f32_e32 v60, v60
	v_rcp_f32_e32 v61, v61
	v_rcp_f32_e32 v62, v62
	v_rcp_f32_e32 v63, v63
	v_cvt_pk_bf16_f32 v132, v64, v65
	v_cvt_pk_bf16_f32 v133, v66, v67
	v_cvt_pk_bf16_f32 v134, v60, v61
	v_cvt_pk_bf16_f32 v135, v62, v63
	global_store_dwordx4 v[2:3], v[132:135], off
	v_med3_f32 v56, v56, s81, v176
	v_med3_f32 v57, v57, s81, v176
	v_med3_f32 v58, v58, s81, v176
	v_med3_f32 v59, v59, s81, v176
	v_med3_f32 v52, v52, s81, v176
	v_med3_f32 v53, v53, s81, v176
	v_med3_f32 v54, v54, s81, v176
	v_med3_f32 v55, v55, s81, v176
	v_pk_mul_f32 v[56:57], v[56:57], s[100:101] op_sel_hi:[1,0]
	v_pk_mul_f32 v[58:59], v[58:59], s[100:101] op_sel_hi:[1,0]
	v_pk_mul_f32 v[52:53], v[52:53], s[100:101] op_sel_hi:[1,0]
	v_pk_mul_f32 v[54:55], v[54:55], s[100:101] op_sel_hi:[1,0]
	v_exp_f32_e32 v56, v56
	v_exp_f32_e32 v57, v57
	v_exp_f32_e32 v58, v58
	v_exp_f32_e32 v59, v59
	v_exp_f32_e32 v52, v52
	v_exp_f32_e32 v53, v53
	v_exp_f32_e32 v54, v54
	v_exp_f32_e32 v55, v55
	v_pk_add_f32 v[56:57], v[56:57], 1.0 op_sel_hi:[1,0]
	v_pk_add_f32 v[58:59], v[58:59], 1.0 op_sel_hi:[1,0]
	v_pk_add_f32 v[52:53], v[52:53], 1.0 op_sel_hi:[1,0]
	v_pk_add_f32 v[54:55], v[54:55], 1.0 op_sel_hi:[1,0]
	v_rcp_f32_e32 v56, v56
	v_rcp_f32_e32 v57, v57
	v_rcp_f32_e32 v58, v58
	v_rcp_f32_e32 v59, v59
	v_rcp_f32_e32 v52, v52
	v_rcp_f32_e32 v53, v53
	v_rcp_f32_e32 v54, v54
	v_rcp_f32_e32 v55, v55
	v_cvt_pk_bf16_f32 v140, v56, v57
	v_cvt_pk_bf16_f32 v141, v58, v59
	v_cvt_pk_bf16_f32 v142, v52, v53
	v_cvt_pk_bf16_f32 v143, v54, v55
	global_store_dwordx4 v[2:3], v[140:143], off offset:1024
	v_lshl_add_u64 v[2:3], v[2:3], 0, s[20:21]
	v_med3_f32 v48, v48, s81, v176
	v_med3_f32 v49, v49, s81, v176
	v_med3_f32 v50, v50, s81, v176
	v_med3_f32 v51, v51, s81, v176
	v_med3_f32 v44, v44, s81, v176
	v_med3_f32 v45, v45, s81, v176
	v_med3_f32 v46, v46, s81, v176
	v_med3_f32 v47, v47, s81, v176
	v_pk_mul_f32 v[48:49], v[48:49], s[100:101] op_sel_hi:[1,0]
	v_pk_mul_f32 v[50:51], v[50:51], s[100:101] op_sel_hi:[1,0]
	v_pk_mul_f32 v[44:45], v[44:45], s[100:101] op_sel_hi:[1,0]
	v_pk_mul_f32 v[46:47], v[46:47], s[100:101] op_sel_hi:[1,0]
	v_exp_f32_e32 v48, v48
	v_exp_f32_e32 v49, v49
	v_exp_f32_e32 v50, v50
	v_exp_f32_e32 v51, v51
	v_exp_f32_e32 v44, v44
	v_exp_f32_e32 v45, v45
	v_exp_f32_e32 v46, v46
	v_exp_f32_e32 v47, v47
	v_pk_add_f32 v[48:49], v[48:49], 1.0 op_sel_hi:[1,0]
	v_pk_add_f32 v[50:51], v[50:51], 1.0 op_sel_hi:[1,0]
	v_pk_add_f32 v[44:45], v[44:45], 1.0 op_sel_hi:[1,0]
	v_pk_add_f32 v[46:47], v[46:47], 1.0 op_sel_hi:[1,0]
	v_rcp_f32_e32 v48, v48
	v_rcp_f32_e32 v49, v49
	v_rcp_f32_e32 v50, v50
	v_rcp_f32_e32 v51, v51
	v_rcp_f32_e32 v44, v44
	v_rcp_f32_e32 v45, v45
	v_rcp_f32_e32 v46, v46
	v_rcp_f32_e32 v47, v47
	v_cvt_pk_bf16_f32 v132, v48, v49
	v_cvt_pk_bf16_f32 v133, v50, v51
	v_cvt_pk_bf16_f32 v134, v44, v45
	v_cvt_pk_bf16_f32 v135, v46, v47
	global_store_dwordx4 v[2:3], v[132:135], off
	v_med3_f32 v40, v40, s81, v176
	v_med3_f32 v41, v41, s81, v176
	v_med3_f32 v42, v42, s81, v176
	v_med3_f32 v43, v43, s81, v176
	v_med3_f32 v36, v36, s81, v176
	v_med3_f32 v37, v37, s81, v176
	v_med3_f32 v38, v38, s81, v176
	v_med3_f32 v39, v39, s81, v176
	v_pk_mul_f32 v[40:41], v[40:41], s[100:101] op_sel_hi:[1,0]
	v_pk_mul_f32 v[42:43], v[42:43], s[100:101] op_sel_hi:[1,0]
	v_pk_mul_f32 v[36:37], v[36:37], s[100:101] op_sel_hi:[1,0]
	v_pk_mul_f32 v[38:39], v[38:39], s[100:101] op_sel_hi:[1,0]
	v_exp_f32_e32 v40, v40
	v_exp_f32_e32 v41, v41
	v_exp_f32_e32 v42, v42
	v_exp_f32_e32 v43, v43
	v_exp_f32_e32 v36, v36
	v_exp_f32_e32 v37, v37
	v_exp_f32_e32 v38, v38
	v_exp_f32_e32 v39, v39
	v_pk_add_f32 v[40:41], v[40:41], 1.0 op_sel_hi:[1,0]
	v_pk_add_f32 v[42:43], v[42:43], 1.0 op_sel_hi:[1,0]
	v_pk_add_f32 v[36:37], v[36:37], 1.0 op_sel_hi:[1,0]
	v_pk_add_f32 v[38:39], v[38:39], 1.0 op_sel_hi:[1,0]
	v_rcp_f32_e32 v40, v40
	v_rcp_f32_e32 v41, v41
	v_rcp_f32_e32 v42, v42
	v_rcp_f32_e32 v43, v43
	v_rcp_f32_e32 v36, v36
	v_rcp_f32_e32 v37, v37
	v_rcp_f32_e32 v38, v38
	v_rcp_f32_e32 v39, v39
	v_cvt_pk_bf16_f32 v140, v40, v41
	v_cvt_pk_bf16_f32 v141, v42, v43
	v_cvt_pk_bf16_f32 v142, v36, v37
	v_cvt_pk_bf16_f32 v143, v38, v39
	global_store_dwordx4 v[2:3], v[140:143], off offset:1024
	v_lshl_add_u64 v[2:3], v[2:3], 0, s[20:21]
	v_med3_f32 v32, v32, s81, v176
	v_med3_f32 v33, v33, s81, v176
	v_med3_f32 v34, v34, s81, v176
	v_med3_f32 v35, v35, s81, v176
	v_med3_f32 v28, v28, s81, v176
	v_med3_f32 v29, v29, s81, v176
	v_med3_f32 v30, v30, s81, v176
	v_med3_f32 v31, v31, s81, v176
	v_pk_mul_f32 v[32:33], v[32:33], s[100:101] op_sel_hi:[1,0]
	v_pk_mul_f32 v[34:35], v[34:35], s[100:101] op_sel_hi:[1,0]
	v_pk_mul_f32 v[28:29], v[28:29], s[100:101] op_sel_hi:[1,0]
	v_pk_mul_f32 v[30:31], v[30:31], s[100:101] op_sel_hi:[1,0]
	v_exp_f32_e32 v32, v32
	v_exp_f32_e32 v33, v33
	v_exp_f32_e32 v34, v34
	v_exp_f32_e32 v35, v35
	v_exp_f32_e32 v28, v28
	v_exp_f32_e32 v29, v29
	v_exp_f32_e32 v30, v30
	v_exp_f32_e32 v31, v31
	v_pk_add_f32 v[32:33], v[32:33], 1.0 op_sel_hi:[1,0]
	v_pk_add_f32 v[34:35], v[34:35], 1.0 op_sel_hi:[1,0]
	v_pk_add_f32 v[28:29], v[28:29], 1.0 op_sel_hi:[1,0]
	v_pk_add_f32 v[30:31], v[30:31], 1.0 op_sel_hi:[1,0]
	v_rcp_f32_e32 v32, v32
	v_rcp_f32_e32 v33, v33
	v_rcp_f32_e32 v34, v34
	v_rcp_f32_e32 v35, v35
	v_rcp_f32_e32 v28, v28
	v_rcp_f32_e32 v29, v29
	v_rcp_f32_e32 v30, v30
	v_rcp_f32_e32 v31, v31
	v_cvt_pk_bf16_f32 v132, v32, v33
	v_cvt_pk_bf16_f32 v133, v34, v35
	v_cvt_pk_bf16_f32 v134, v28, v29
	v_cvt_pk_bf16_f32 v135, v30, v31
	global_store_dwordx4 v[2:3], v[132:135], off
	v_med3_f32 v24, v24, s81, v176
	v_med3_f32 v25, v25, s81, v176
	v_med3_f32 v26, v26, s81, v176
	v_med3_f32 v27, v27, s81, v176
	v_med3_f32 v20, v20, s81, v176
	v_med3_f32 v21, v21, s81, v176
	v_med3_f32 v22, v22, s81, v176
	v_med3_f32 v23, v23, s81, v176
	v_pk_mul_f32 v[24:25], v[24:25], s[100:101] op_sel_hi:[1,0]
	v_pk_mul_f32 v[26:27], v[26:27], s[100:101] op_sel_hi:[1,0]
	v_pk_mul_f32 v[20:21], v[20:21], s[100:101] op_sel_hi:[1,0]
	v_pk_mul_f32 v[22:23], v[22:23], s[100:101] op_sel_hi:[1,0]
	v_exp_f32_e32 v24, v24
	v_exp_f32_e32 v25, v25
	v_exp_f32_e32 v26, v26
	v_exp_f32_e32 v27, v27
	v_exp_f32_e32 v20, v20
	v_exp_f32_e32 v21, v21
	v_exp_f32_e32 v22, v22
	v_exp_f32_e32 v23, v23
	v_pk_add_f32 v[24:25], v[24:25], 1.0 op_sel_hi:[1,0]
	v_pk_add_f32 v[26:27], v[26:27], 1.0 op_sel_hi:[1,0]
	v_pk_add_f32 v[20:21], v[20:21], 1.0 op_sel_hi:[1,0]
	v_pk_add_f32 v[22:23], v[22:23], 1.0 op_sel_hi:[1,0]
	v_rcp_f32_e32 v24, v24
	v_rcp_f32_e32 v25, v25
	v_rcp_f32_e32 v26, v26
	v_rcp_f32_e32 v27, v27
	v_rcp_f32_e32 v20, v20
	v_rcp_f32_e32 v21, v21
	v_rcp_f32_e32 v22, v22
	v_rcp_f32_e32 v23, v23
	v_cvt_pk_bf16_f32 v140, v24, v25
	v_cvt_pk_bf16_f32 v141, v26, v27
	v_cvt_pk_bf16_f32 v142, v20, v21
	v_cvt_pk_bf16_f32 v143, v22, v23
	global_store_dwordx4 v[2:3], v[140:143], off offset:1024
	v_lshl_add_u64 v[2:3], v[2:3], 0, s[20:21]
	v_med3_f32 v16, v16, s81, v176
	v_med3_f32 v17, v17, s81, v176
	v_med3_f32 v18, v18, s81, v176
	v_med3_f32 v19, v19, s81, v176
	v_med3_f32 v12, v12, s81, v176
	v_med3_f32 v13, v13, s81, v176
	v_med3_f32 v14, v14, s81, v176
	v_med3_f32 v15, v15, s81, v176
	v_pk_mul_f32 v[16:17], v[16:17], s[100:101] op_sel_hi:[1,0]
	v_pk_mul_f32 v[18:19], v[18:19], s[100:101] op_sel_hi:[1,0]
	v_pk_mul_f32 v[12:13], v[12:13], s[100:101] op_sel_hi:[1,0]
	v_pk_mul_f32 v[14:15], v[14:15], s[100:101] op_sel_hi:[1,0]
	v_exp_f32_e32 v16, v16
	v_exp_f32_e32 v17, v17
	v_exp_f32_e32 v18, v18
	v_exp_f32_e32 v19, v19
	v_exp_f32_e32 v12, v12
	v_exp_f32_e32 v13, v13
	v_exp_f32_e32 v14, v14
	v_exp_f32_e32 v15, v15
	v_pk_add_f32 v[16:17], v[16:17], 1.0 op_sel_hi:[1,0]
	v_pk_add_f32 v[18:19], v[18:19], 1.0 op_sel_hi:[1,0]
	v_pk_add_f32 v[12:13], v[12:13], 1.0 op_sel_hi:[1,0]
	v_pk_add_f32 v[14:15], v[14:15], 1.0 op_sel_hi:[1,0]
	v_rcp_f32_e32 v16, v16
	v_rcp_f32_e32 v17, v17
	v_rcp_f32_e32 v18, v18
	v_rcp_f32_e32 v19, v19
	v_rcp_f32_e32 v12, v12
	v_rcp_f32_e32 v13, v13
	v_rcp_f32_e32 v14, v14
	v_rcp_f32_e32 v15, v15
	v_cvt_pk_bf16_f32 v132, v16, v17
	v_cvt_pk_bf16_f32 v133, v18, v19
	v_cvt_pk_bf16_f32 v134, v12, v13
	v_cvt_pk_bf16_f32 v135, v14, v15
	global_store_dwordx4 v[2:3], v[132:135], off
	v_med3_f32 v136, v6, s81, v176
	v_med3_f32 v137, v7, s81, v176
	v_mov_b32_e32 v138, 0
	v_mov_b32_e32 v139, 0
	v_med3_f32 v8, v8, s81, v176
	v_med3_f32 v9, v9, s81, v176
	v_med3_f32 v10, v10, s81, v176
	v_med3_f32 v11, v11, s81, v176
	v_med3_f32 v4, v4, s81, v176
	v_med3_f32 v5, v5, s81, v176
	v_pk_mul_f32 v[8:9], v[8:9], s[100:101] op_sel_hi:[1,0]
	v_pk_mul_f32 v[10:11], v[10:11], s[100:101] op_sel_hi:[1,0]
	v_pk_mul_f32 v[4:5], v[4:5], s[100:101] op_sel_hi:[1,0]
	v_pk_mul_f32 v[136:137], v[136:137], s[100:101] op_sel_hi:[1,0]
	v_exp_f32_e32 v8, v8
	v_exp_f32_e32 v9, v9
	v_exp_f32_e32 v10, v10
	v_exp_f32_e32 v11, v11
	v_exp_f32_e32 v4, v4
	v_exp_f32_e32 v5, v5
	v_exp_f32_e32 v136, v136
	v_exp_f32_e32 v137, v137
	v_pk_add_f32 v[8:9], v[8:9], 1.0 op_sel_hi:[1,0]
	v_pk_add_f32 v[10:11], v[10:11], 1.0 op_sel_hi:[1,0]
	v_pk_add_f32 v[4:5], v[4:5], 1.0 op_sel_hi:[1,0]
	v_pk_add_f32 v[136:137], v[136:137], 1.0 op_sel_hi:[1,0]
	v_rcp_f32_e32 v8, v8
	v_rcp_f32_e32 v9, v9
	v_rcp_f32_e32 v10, v10
	v_rcp_f32_e32 v11, v11
	v_rcp_f32_e32 v4, v4
	v_rcp_f32_e32 v5, v5
	v_rcp_f32_e32 v136, v136
	v_rcp_f32_e32 v137, v137
	v_cvt_pk_bf16_f32 v132, v8, v9
	v_cvt_pk_bf16_f32 v133, v10, v11
	v_cvt_pk_bf16_f32 v134, v4, v5
	s_mov_b64 s[100:101], 0x300
	v_lshl_add_u64 v[2:3], v[2:3], 0, s[100:101]
.LBB0_607:
	v_cvt_pk_bf16_f32 v135, v136, v137
	s_andn2_b64 vcc, exec, s[54:55]
	s_mov_b64 s[54:55], -1
	global_store_dwordx4 v[2:3], v[132:135], off offset:256
	s_cbranch_vccnz .LBB0_589
	s_andn2_b64 vcc, exec, s[12:13]
	s_cbranch_vccnz .LBB0_588
	s_barrier
	s_branch .LBB0_588
